# DSA loop: first K fragment reads issued right behind the barrier, K/V tile global loads two tiles ahead (two staging register sets, loop unrolled x2) and issued inside the S_A MFMA gaps
# baseline (speedup 1.0000x reference)
; #define LAS __attribute__((address_space(3)))
; #define LDS_WAIT() asm volatile("s_waitcnt lgkmcnt(0)" ::: "memory")
; __device__ __forceinline__ void dsa_unit(const bf16* QB, const int* SEL, bf16* AO, int b, int kvh, int t, LAS unsigned char* wl, int lane) {
;     ...
;     int sidx[8];
; #pragma unroll
;     for (int kb = 0; kb < 8; ++kb) { const int p = 32 * kb + n; sidx[kb] = (p < nsel) ? SEL[row * 256 + p] : 0; }
;     bf16x8 qf[4];
;     { const bf16* qp = QB + row * NBP + CQ + (kvh * 4 + (l15 & 3)) * 128 + 8 * kq;
; #pragma unroll
;       for (int ks = 0; ks < 4; ++ks) qf[ks] = *(const bf16x8*)(qp + 32 * ks); }
;     if (hi == 0) {
; #pragma unroll
;         for (int kb = 0; kb < 8; ++kb) il[32 * kb + n] = sidx[kb];
;     }
;     LDS_WAIT();
;     const int r4 = kq, c16 = l15;
;     const bf16* kg = QB + rowbase * NBP + CK + kvh * 128 + c16 * 8;
;     const bf16* vg = QB + rowbase * NBP + CV + kvh * 128 + c16 * 8;
;     bf16x8 kr[3][8];
; #pragma unroll
;     for (int pb = 0; pb < 3; ++pb)
; #pragma unroll
;         for (int i = 0; i < 8; ++i) kr[pb][i] = *(const bf16x8*)(kg + (size_t)il[32 * pb + 4 * i + r4] * NBP);
;     float lg[8][4];
;     float mx[4] = {-__builtin_inff(), -__builtin_inff(), -__builtin_inff(), -__builtin_inff()};
;     LAS unsigned char* kdst = buf + r4 * 272 + c16 * 16;
;     const LAS unsigned char* kfb = buf + l15 * 272 + 16 * kq;
.Ldsa_selld_end:
	v_mov_b32_e32 v64, 0
	v_mov_b32_e32 v65, 0
	v_mov_b32_e32 v66, 0
	v_mov_b32_e32 v67, 0
	v_lshlrev_b32_e32 v179, 6, v206
	s_lshl_b32 s24, s0, 12
	s_add_u32 s24, s24, 0x11800
	v_add_u32_e32 v179, s24, v179
	ds_write_b128 v179, v[64:67] offset:0
	ds_write_b128 v179, v[64:67] offset:16
	ds_write_b128 v179, v[64:67] offset:32
	ds_write_b128 v179, v[64:67] offset:48
	v_lshrrev_b32_e32 v178, 4, v207
	v_add_u32_e32 v178, s4, v178
	v_and_b32_e32 v179, 15, v207
	v_lshlrev_b32_e32 v182, 4, v179
	s_lshl_b32 s24, s5, 8
	s_add_u32 s24, s24, 0x1000
	v_add_u32_e32 v182, s24, v182
	v_lshl_add_u64 v[160:161], s[78:79], 0, v[182:183]
	v_mad_u64_u32 v[160:161], s[12:13], v178, s23, v[160:161]
	s_mov_b32 s24, 0x44000
	s_mov_b32 s25, 0
	v_lshl_add_u64 v[162:163], v[160:161], 0, s[24:25]
	global_load_dwordx4 v[144:147], v[160:161], off
	global_load_dwordx4 v[148:151], v[160:161], off offset:1024
	global_load_dwordx4 v[152:155], v[162:163], off
	global_load_dwordx4 v[156:159], v[162:163], off offset:1024
	s_cmp_gt_u32 s8, 1
	s_cselect_b32 s24, s16, 0
	v_lshl_add_u64 v[160:161], v[160:161], 0, s[24:25]
	v_lshl_add_u64 v[162:163], v[162:163], 0, s[24:25]
	v_and_b32_e32 v64, 31, v206
	v_lshrrev_b32_e32 v65, 2, v64
	v_and_b32_e32 v66, 3, v64
	s_add_u32 s24, s44, s7
	s_add_u32 s24, s24, s4
	v_add_u32_e32 v178, s24, v65
	s_lshl_b32 s25, s5, 2
	v_add_u32_e32 v179, s25, v66
	v_lshlrev_b32_e32 v179, 8, v179
	v_lshl_add_u32 v182, v175, 1, v179
	v_lshl_add_u64 v[128:129], s[78:79], 0, v[182:183]
	v_mad_u64_u32 v[128:129], s[12:13], v178, s23, v[128:129]
	global_load_dwordx4 v[80:83], v[128:129], off offset:0
	global_load_dwordx4 v[84:87], v[128:129], off offset:32
	global_load_dwordx4 v[88:91], v[128:129], off offset:64
	global_load_dwordx4 v[92:95], v[128:129], off offset:96
	global_load_dwordx4 v[96:99], v[128:129], off offset:128
	global_load_dwordx4 v[100:103], v[128:129], off offset:160
	global_load_dwordx4 v[104:107], v[128:129], off offset:192
	global_load_dwordx4 v[108:111], v[128:129], off offset:224
	v_add_u32_e32 v178, s44, v65
	v_lshlrev_b32_e32 v172, 9, v178
	v_add_u32_e32 v172, 0x11800, v172
	s_add_u32 s24, s44, s7
	v_add_u32_e32 v178, s24, v65
	v_sub_u32_e32 v178, v175, v178
	v_add_u32_e32 v178, 0x80, v178
	v_lshlrev_b32_e32 v178, 2, v178
	v_lshl_add_u32 v177, v66, 10, v178
	v_add_u32_e32 v177, 0x1a400, v177
	s_sub_u32 s19, s24, 0x7a
	s_lshl_b32 s25, s5, 2
	v_add_u32_e32 v178, s25, v66
	v_lshlrev_b32_e32 v178, 7, v178
	v_add_u32_e32 v176, 0x1983c, v178
	ds_read_b32 v176, v176
	v_and_b32_e32 v64, 0xff, v207
	v_subrev_u32_e32 v65, 0x80, v64
	v_sub_u32_e32 v66, 0, v65
	v_max_i32_e32 v66, v65, v66
	v_mov_b32_e32 v67, 8
	v_cmp_le_i32_e32 vcc, 12, v66
	s_nop 1
	v_addc_co_u32_e32 v67, vcc, 0, v67, vcc
	v_cmp_le_i32_e32 vcc, 16, v66
	s_nop 1
	v_addc_co_u32_e32 v67, vcc, 0, v67, vcc
	v_cmp_le_i32_e32 vcc, 23, v66
	s_nop 1
	v_addc_co_u32_e32 v67, vcc, 0, v67, vcc
	v_cmp_le_i32_e32 vcc, 32, v66
	s_nop 1
	v_addc_co_u32_e32 v67, vcc, 0, v67, vcc
	v_cmp_le_i32_e32 vcc, 46, v66
	s_nop 1
	v_addc_co_u32_e32 v67, vcc, 0, v67, vcc
	v_cmp_le_i32_e32 vcc, 64, v66
	s_nop 1
	v_addc_co_u32_e32 v67, vcc, 0, v67, vcc
	v_cmp_le_i32_e32 vcc, 91, v66
	s_nop 1
	v_addc_co_u32_e32 v67, vcc, 0, v67, vcc
	v_cmp_gt_i32_e32 vcc, 8, v66
	s_nop 1
	v_cndmask_b32_e32 v67, v67, v66, vcc
	v_add_u32_e32 v68, 16, v67
	v_cmp_lt_i32_e32 vcc, 0, v65
	s_nop 1
	v_cndmask_b32_e32 v67, v67, v68, vcc
	v_lshrrev_b32_e32 v68, 8, v207
	s_lshl_b32 s24, s5, 2
	v_add_u32_e32 v69, s24, v68
	v_lshl_add_u32 v69, v69, 5, v67
	v_lshlrev_b32_e32 v69, 2, v69
	v_add_u32_e32 v69, 0x19800, v69
	ds_read_b32 v70, v69
	ds_read_b32 v71, v69 offset:256
	v_lshl_add_u32 v72, v68, 8, v64
	v_lshlrev_b32_e32 v72, 2, v72
	v_add_u32_e32 v72, 0x1a400, v72
	s_waitcnt lgkmcnt(0)
	ds_write_b32 v72, v70
	ds_write_b32 v72, v71 offset:2048
	s_waitcnt vmcnt(0)
	global_load_dwordx4 v[188:191], v[160:161], off
	global_load_dwordx4 v[192:195], v[160:161], off offset:1024
	global_load_dwordx4 v[196:199], v[162:163], off
	global_load_dwordx4 v[200:203], v[162:163], off offset:1024
	s_mov_b32 s41, 0
	s_cmp_gt_u32 s8, 2
	s_cselect_b32 s40, s16, 0
	v_lshl_add_u64 v[160:161], v[160:161], 0, s[40:41]
	v_lshl_add_u64 v[162:163], v[162:163], 0, s[40:41]
	s_lshl_b32 s24, s0, 12
	s_add_u32 s24, s24, 0x11800
	v_lshrrev_b32_e32 v64, 3, v0
	v_and_b32_e32 v64, 0x1fc, v64
	v_add_u32_e32 v64, s24, v64
	v_lshlrev_b32_e64 v65, v0, 1
	ds_or_b32 v64, v65 offset:0
	v_lshrrev_b32_e32 v64, 3, v1
	v_and_b32_e32 v64, 0x1fc, v64
	v_add_u32_e32 v64, s24, v64
	v_lshlrev_b32_e64 v65, v1, 1
	ds_or_b32 v64, v65 offset:512
	v_lshrrev_b32_e32 v64, 3, v2
	v_and_b32_e32 v64, 0x1fc, v64
	v_add_u32_e32 v64, s24, v64
	v_lshlrev_b32_e64 v65, v2, 1
	ds_or_b32 v64, v65 offset:1024
	v_lshrrev_b32_e32 v64, 3, v3
	v_and_b32_e32 v64, 0x1fc, v64
	v_add_u32_e32 v64, s24, v64
	v_lshlrev_b32_e64 v65, v3, 1
	ds_or_b32 v64, v65 offset:1536
	v_lshrrev_b32_e32 v64, 3, v4
	v_and_b32_e32 v64, 0x1fc, v64
	v_add_u32_e32 v64, s24, v64
	v_lshlrev_b32_e64 v65, v4, 1
	ds_or_b32 v64, v65 offset:2048
	v_lshrrev_b32_e32 v64, 3, v5
	v_and_b32_e32 v64, 0x1fc, v64
	v_add_u32_e32 v64, s24, v64
	v_lshlrev_b32_e64 v65, v5, 1
	ds_or_b32 v64, v65 offset:2560
	v_lshrrev_b32_e32 v64, 3, v6
	v_and_b32_e32 v64, 0x1fc, v64
	v_add_u32_e32 v64, s24, v64
	v_lshlrev_b32_e64 v65, v6, 1
	ds_or_b32 v64, v65 offset:3072
	v_lshrrev_b32_e32 v64, 3, v7
	v_and_b32_e32 v64, 0x1fc, v64
	v_add_u32_e32 v64, s24, v64
	v_lshlrev_b32_e64 v65, v7, 1
	ds_or_b32 v64, v65 offset:3584
	s_cmp_gt_u32 s43, 1
	s_cbranch_scc0 .Ldsa_selor_end
; __device__ __forceinline__ void dsa_unit(const bf16* QB, const int* SEL, bf16* AO, int b, int kvh, int t, LAS unsigned char* wl, int lane) {
;     ...
;     int sidx[8];
; #pragma unroll
;     for (int kb = 0; kb < 8; ++kb) { const int p = 32 * kb + n; sidx[kb] = (p < nsel) ? SEL[row * 256 + p] : 0; }
;     bf16x8 qf[4];
;     { const bf16* qp = QB + row * NBP + CQ + (kvh * 4 + (l15 & 3)) * 128 + 8 * kq;
; #pragma unroll
;       for (int ks = 0; ks < 4; ++ks) qf[ks] = *(const bf16x8*)(qp + 32 * ks); }
;     if (hi == 0) {
; #pragma unroll
;         for (int kb = 0; kb < 8; ++kb) il[32 * kb + n] = sidx[kb];
;     }
	v_lshrrev_b32_e32 v64, 3, v8
	v_and_b32_e32 v64, 0x1fc, v64
	v_add_u32_e32 v64, s24, v64
	v_lshlrev_b32_e64 v65, v8, 1
	ds_or_b32 v64, v65 offset:0
	v_lshrrev_b32_e32 v64, 3, v9
	v_and_b32_e32 v64, 0x1fc, v64
	v_add_u32_e32 v64, s24, v64
	v_lshlrev_b32_e64 v65, v9, 1
	ds_or_b32 v64, v65 offset:512
	v_lshrrev_b32_e32 v64, 3, v10
	v_and_b32_e32 v64, 0x1fc, v64
	v_add_u32_e32 v64, s24, v64
	v_lshlrev_b32_e64 v65, v10, 1
	ds_or_b32 v64, v65 offset:1024
	v_lshrrev_b32_e32 v64, 3, v11
	v_and_b32_e32 v64, 0x1fc, v64
	v_add_u32_e32 v64, s24, v64
	v_lshlrev_b32_e64 v65, v11, 1
	ds_or_b32 v64, v65 offset:1536
	v_lshrrev_b32_e32 v64, 3, v12
	v_and_b32_e32 v64, 0x1fc, v64
	v_add_u32_e32 v64, s24, v64
	v_lshlrev_b32_e64 v65, v12, 1
	ds_or_b32 v64, v65 offset:2048
	v_lshrrev_b32_e32 v64, 3, v13
	v_and_b32_e32 v64, 0x1fc, v64
	v_add_u32_e32 v64, s24, v64
	v_lshlrev_b32_e64 v65, v13, 1
	ds_or_b32 v64, v65 offset:2560
	v_lshrrev_b32_e32 v64, 3, v14
	v_and_b32_e32 v64, 0x1fc, v64
	v_add_u32_e32 v64, s24, v64
	v_lshlrev_b32_e64 v65, v14, 1
	ds_or_b32 v64, v65 offset:3072
	v_lshrrev_b32_e32 v64, 3, v15
	v_and_b32_e32 v64, 0x1fc, v64
	v_add_u32_e32 v64, s24, v64
	v_lshlrev_b32_e64 v65, v15, 1
	ds_or_b32 v64, v65 offset:3584
	s_cmp_gt_u32 s43, 2
	s_cbranch_scc0 .Ldsa_selor_end
	v_lshrrev_b32_e32 v64, 3, v16
	v_and_b32_e32 v64, 0x1fc, v64
	v_add_u32_e32 v64, s24, v64
	v_lshlrev_b32_e64 v65, v16, 1
	ds_or_b32 v64, v65 offset:0
	v_lshrrev_b32_e32 v64, 3, v17
	v_and_b32_e32 v64, 0x1fc, v64
	v_add_u32_e32 v64, s24, v64
	v_lshlrev_b32_e64 v65, v17, 1
	ds_or_b32 v64, v65 offset:512
	v_lshrrev_b32_e32 v64, 3, v18
	v_and_b32_e32 v64, 0x1fc, v64
	v_add_u32_e32 v64, s24, v64
	v_lshlrev_b32_e64 v65, v18, 1
	ds_or_b32 v64, v65 offset:1024
	v_lshrrev_b32_e32 v64, 3, v19
	v_and_b32_e32 v64, 0x1fc, v64
	v_add_u32_e32 v64, s24, v64
	v_lshlrev_b32_e64 v65, v19, 1
	ds_or_b32 v64, v65 offset:1536
	v_lshrrev_b32_e32 v64, 3, v20
	v_and_b32_e32 v64, 0x1fc, v64
	v_add_u32_e32 v64, s24, v64
	v_lshlrev_b32_e64 v65, v20, 1
	ds_or_b32 v64, v65 offset:2048
	v_lshrrev_b32_e32 v64, 3, v21
	v_and_b32_e32 v64, 0x1fc, v64
	v_add_u32_e32 v64, s24, v64
	v_lshlrev_b32_e64 v65, v21, 1
	ds_or_b32 v64, v65 offset:2560
	v_lshrrev_b32_e32 v64, 3, v22
	v_and_b32_e32 v64, 0x1fc, v64
	v_add_u32_e32 v64, s24, v64
	v_lshlrev_b32_e64 v65, v22, 1
	ds_or_b32 v64, v65 offset:3072
	v_lshrrev_b32_e32 v64, 3, v23
	v_and_b32_e32 v64, 0x1fc, v64
	v_add_u32_e32 v64, s24, v64
	v_lshlrev_b32_e64 v65, v23, 1
	ds_or_b32 v64, v65 offset:3584
	s_cmp_gt_u32 s43, 3
	s_cbranch_scc0 .Ldsa_selor_end
	v_lshrrev_b32_e32 v64, 3, v24
	v_and_b32_e32 v64, 0x1fc, v64
	v_add_u32_e32 v64, s24, v64
	v_lshlrev_b32_e64 v65, v24, 1
	ds_or_b32 v64, v65 offset:0
	v_lshrrev_b32_e32 v64, 3, v25
	v_and_b32_e32 v64, 0x1fc, v64
	v_add_u32_e32 v64, s24, v64
	v_lshlrev_b32_e64 v65, v25, 1
	ds_or_b32 v64, v65 offset:512
	v_lshrrev_b32_e32 v64, 3, v26
	v_and_b32_e32 v64, 0x1fc, v64
	v_add_u32_e32 v64, s24, v64
	v_lshlrev_b32_e64 v65, v26, 1
	ds_or_b32 v64, v65 offset:1024
	v_lshrrev_b32_e32 v64, 3, v27
	v_and_b32_e32 v64, 0x1fc, v64
	v_add_u32_e32 v64, s24, v64
	v_lshlrev_b32_e64 v65, v27, 1
	ds_or_b32 v64, v65 offset:1536
	v_lshrrev_b32_e32 v64, 3, v28
	v_and_b32_e32 v64, 0x1fc, v64
	v_add_u32_e32 v64, s24, v64
	v_lshlrev_b32_e64 v65, v28, 1
	ds_or_b32 v64, v65 offset:2048
	v_lshrrev_b32_e32 v64, 3, v29
	v_and_b32_e32 v64, 0x1fc, v64
	v_add_u32_e32 v64, s24, v64
	v_lshlrev_b32_e64 v65, v29, 1
	ds_or_b32 v64, v65 offset:2560
	v_lshrrev_b32_e32 v64, 3, v30
	v_and_b32_e32 v64, 0x1fc, v64
	v_add_u32_e32 v64, s24, v64
	v_lshlrev_b32_e64 v65, v30, 1
	ds_or_b32 v64, v65 offset:3072
	v_lshrrev_b32_e32 v64, 3, v31
	v_and_b32_e32 v64, 0x1fc, v64
	v_add_u32_e32 v64, s24, v64
	v_lshlrev_b32_e64 v65, v31, 1
	ds_or_b32 v64, v65 offset:3584

; #define LAS __attribute__((address_space(3)))
; #define LDS_WAIT() asm volatile("s_waitcnt lgkmcnt(0)" ::: "memory")
; __device__ __forceinline__ void dsa_unit(const bf16* QB, const int* SEL, bf16* AO, int b, int kvh, int t, LAS unsigned char* wl, int lane) {
;     ...
;     for (int kb = 0; kb < 8; ++kb) {
; #pragma unroll
;         for (int i = 0; i < 8; ++i) *(LAS bf16x8*)(kdst + (4 * i) * 272) = kr[kb % 3][i];
;         if (kb + 3 < 8) {
; #pragma unroll
;             for (int i = 0; i < 8; ++i) kr[kb % 3][i] = *(const bf16x8*)(kg + (size_t)il[32 * (kb + 3) + 4 * i + r4] * NBP);
;         }
;         LDS_WAIT();
;         f32x4v a0 = {0.f, 0.f, 0.f, 0.f}, a1 = {0.f, 0.f, 0.f, 0.f};
; #pragma unroll
;         for (int ks = 0; ks < 4; ++ks) { const bf16x8 b0 = *(const LAS bf16x8*)(kfb + 64 * ks), b1 = *(const LAS bf16x8*)(kfb + 16 * 272 + 64 * ks);
;             a0 = __builtin_amdgcn_mfma_f32_16x16x32_bf16(qf[ks], b0, a0, 0, 0, 0); a1 = __builtin_amdgcn_mfma_f32_16x16x32_bf16(qf[ks], b1, a1, 0, 0, 0); }
;         LDS_WAIT();
;         const int bk = t5_bucket(sidx[kb] - t);
;         const bool valid = (32 * kb + n) < nsel;
; #pragma unroll
;         for (int g = 0; g < 4; ++g) { const float raw = upper ? a1[g] : a0[g]; const float v = valid ? raw + bl[g * 32 + bk] : -__builtin_inff(); lg[kb][g] = v; mx[g] = __builtin_fmaxf(mx[g], v); }
;     }
.Ldsa_it:
	v_add_u32_e32 v168, s10, v164
	ds_read_b128 v[112:115], v168 offset:0
	ds_read_b128 v[116:119], v168 offset:32
	ds_read_b128 v[120:123], v168 offset:64
	ds_read_b128 v[124:127], v168 offset:96
	v_add_u32_e32 v169, s10, v165
	v_add_u32_e32 v170, s11, v166
	v_add_u32_e32 v171, s11, v167
	s_add_u32 s24, s9, 1
	s_lshl_b32 s20, s9, 6
	s_add_u32 s27, s20, 32
	v_lshrrev_b32_e32 v182, v175, v182
	s_cmp_le_i32 s20, s19
	s_cbranch_scc1 .Ldsa_farA0
	s_lshl_b32 s26, s20, 2
	v_add_u32_e32 v179, s26, v177
	ds_read_b32 v64, v179 offset:0
	ds_read_b32 v65, v179 offset:4
	ds_read_b32 v66, v179 offset:8
	ds_read_b32 v67, v179 offset:12
	ds_read_b32 v68, v179 offset:16
	ds_read_b32 v69, v179 offset:20
	ds_read_b32 v70, v179 offset:24
	ds_read_b32 v71, v179 offset:28
	ds_read_b32 v72, v179 offset:64
	ds_read_b32 v73, v179 offset:68
	ds_read_b32 v74, v179 offset:72
	ds_read_b32 v75, v179 offset:76
	ds_read_b32 v76, v179 offset:80
	ds_read_b32 v77, v179 offset:84
	ds_read_b32 v78, v179 offset:88
	ds_read_b32 v79, v179 offset:92
	s_waitcnt lgkmcnt(0)
	v_bfe_i32 v178, v174, 0, 1
	v_bfi_b32 v64, v178, v64, s13
	v_bfe_i32 v178, v174, 1, 1
	v_bfi_b32 v65, v178, v65, s13
	v_bfe_i32 v178, v174, 2, 1
	v_bfi_b32 v66, v178, v66, s13
	v_bfe_i32 v178, v174, 3, 1
	v_bfi_b32 v67, v178, v67, s13
	v_bfe_i32 v178, v174, 4, 1
	v_bfi_b32 v68, v178, v68, s13
	v_bfe_i32 v178, v174, 5, 1
	v_bfi_b32 v69, v178, v69, s13
	v_bfe_i32 v178, v174, 6, 1
	v_bfi_b32 v70, v178, v70, s13
	v_bfe_i32 v178, v174, 7, 1
	v_bfi_b32 v71, v178, v71, s13
	v_bfe_i32 v178, v174, 16, 1
	v_bfi_b32 v72, v178, v72, s13
	v_bfe_i32 v178, v174, 17, 1
	v_bfi_b32 v73, v178, v73, s13
	v_bfe_i32 v178, v174, 18, 1
	v_bfi_b32 v74, v178, v74, s13
	v_bfe_i32 v178, v174, 19, 1
	v_bfi_b32 v75, v178, v75, s13
	v_bfe_i32 v178, v174, 20, 1
	v_bfi_b32 v76, v178, v76, s13
	v_bfe_i32 v178, v174, 21, 1
	v_bfi_b32 v77, v178, v77, s13
	v_bfe_i32 v178, v174, 22, 1
	v_bfi_b32 v78, v178, v78, s13
	v_bfe_i32 v178, v174, 23, 1
	v_bfi_b32 v79, v178, v79, s13
	s_nop 1
.Ldsa_farA0:
	s_waitcnt lgkmcnt(3)
	v_mfma_f32_32x32x16_bf16 v[64:79], v[112:115], v[80:83], v[64:79]
	ds_read_b128 v[112:115], v168 offset:128
	v_bfe_i32 v178, v182, 0, 1
	v_bfi_b32 v128, v178, v176, s13
	v_bfe_i32 v179, v182, 1, 1
	v_bfi_b32 v129, v179, v176, s13
	s_waitcnt lgkmcnt(3)
	v_mfma_f32_32x32x16_bf16 v[64:79], v[116:119], v[84:87], v[64:79]
	ds_read_b128 v[116:119], v168 offset:160
	v_bfe_i32 v178, v182, 2, 1
	v_bfi_b32 v130, v178, v176, s13
	v_bfe_i32 v179, v182, 3, 1
	v_bfi_b32 v131, v179, v176, s13
	global_load_dwordx4 v[144:147], v[160:161], off
	s_waitcnt lgkmcnt(3)
	v_mfma_f32_32x32x16_bf16 v[64:79], v[120:123], v[88:91], v[64:79]
	ds_read_b128 v[120:123], v168 offset:192
	v_bfe_i32 v178, v182, 4, 1
	v_bfi_b32 v132, v178, v176, s13
	v_bfe_i32 v179, v182, 5, 1
	v_bfi_b32 v133, v179, v176, s13
	global_load_dwordx4 v[148:151], v[160:161], off offset:1024
	s_waitcnt lgkmcnt(3)
	v_mfma_f32_32x32x16_bf16 v[64:79], v[124:127], v[92:95], v[64:79]
	ds_read_b128 v[124:127], v168 offset:224
	v_bfe_i32 v178, v182, 6, 1
	v_bfi_b32 v134, v178, v176, s13
	v_bfe_i32 v179, v182, 7, 1
	v_bfi_b32 v135, v179, v176, s13
	global_load_dwordx4 v[152:155], v[162:163], off
	s_waitcnt lgkmcnt(3)
	v_mfma_f32_32x32x16_bf16 v[64:79], v[112:115], v[96:99], v[64:79]
	ds_read_b128 v[112:115], v168 offset:8704
	v_bfe_i32 v178, v182, 16, 1
	v_bfi_b32 v136, v178, v176, s13
	v_bfe_i32 v179, v182, 17, 1
	v_bfi_b32 v137, v179, v176, s13
	global_load_dwordx4 v[156:159], v[162:163], off offset:1024
	s_waitcnt lgkmcnt(3)
	v_mfma_f32_32x32x16_bf16 v[64:79], v[116:119], v[100:103], v[64:79]
	ds_read_b128 v[116:119], v168 offset:8736
	v_bfe_i32 v178, v182, 18, 1
	v_bfi_b32 v138, v178, v176, s13
	v_bfe_i32 v179, v182, 19, 1
	v_bfi_b32 v139, v179, v176, s13
	s_add_u32 s40, s9, 3
	s_cmp_lt_u32 s40, s8
	s_cselect_b32 s40, s16, 0
	v_lshl_add_u64 v[160:161], v[160:161], 0, s[40:41]
	v_lshl_add_u64 v[162:163], v[162:163], 0, s[40:41]
	s_waitcnt lgkmcnt(3)
	v_mfma_f32_32x32x16_bf16 v[64:79], v[120:123], v[104:107], v[64:79]
	ds_read_b128 v[120:123], v168 offset:8768
	v_bfe_i32 v178, v182, 20, 1
	v_bfi_b32 v140, v178, v176, s13
	v_bfe_i32 v179, v182, 21, 1
	v_bfi_b32 v141, v179, v176, s13
	s_waitcnt lgkmcnt(3)
	v_mfma_f32_32x32x16_bf16 v[64:79], v[124:127], v[108:111], v[64:79]
	ds_read_b128 v[124:127], v168 offset:8800
	v_bfe_i32 v178, v182, 22, 1
	v_bfi_b32 v142, v178, v176, s13
	v_bfe_i32 v179, v182, 23, 1
	v_bfi_b32 v143, v179, v176, s13
	s_cmp_le_i32 s27, s19
	s_cbranch_scc1 .Ldsa_farB0
	s_lshl_b32 s26, s27, 2
	v_add_u32_e32 v179, s26, v177
	ds_read_b32 v128, v179 offset:0
	ds_read_b32 v129, v179 offset:4
	ds_read_b32 v130, v179 offset:8
	ds_read_b32 v131, v179 offset:12
	ds_read_b32 v132, v179 offset:16
	ds_read_b32 v133, v179 offset:20
	ds_read_b32 v134, v179 offset:24
	ds_read_b32 v135, v179 offset:28
	ds_read_b32 v136, v179 offset:64
	ds_read_b32 v137, v179 offset:68
	ds_read_b32 v138, v179 offset:72
	ds_read_b32 v139, v179 offset:76
	ds_read_b32 v140, v179 offset:80
	ds_read_b32 v141, v179 offset:84
	ds_read_b32 v142, v179 offset:88
	ds_read_b32 v143, v179 offset:92
	s_waitcnt lgkmcnt(0)
	v_bfe_i32 v178, v182, 0, 1
	v_bfi_b32 v128, v178, v128, s13
	v_bfe_i32 v178, v182, 1, 1
	v_bfi_b32 v129, v178, v129, s13
	v_bfe_i32 v178, v182, 2, 1
	v_bfi_b32 v130, v178, v130, s13
	v_bfe_i32 v178, v182, 3, 1
	v_bfi_b32 v131, v178, v131, s13
	v_bfe_i32 v178, v182, 4, 1
	v_bfi_b32 v132, v178, v132, s13
	v_bfe_i32 v178, v182, 5, 1
	v_bfi_b32 v133, v178, v133, s13
	v_bfe_i32 v178, v182, 6, 1
	v_bfi_b32 v134, v178, v134, s13
	v_bfe_i32 v178, v182, 7, 1
	v_bfi_b32 v135, v178, v135, s13
	v_bfe_i32 v178, v182, 16, 1
	v_bfi_b32 v136, v178, v136, s13
	v_bfe_i32 v178, v182, 17, 1
	v_bfi_b32 v137, v178, v137, s13
	v_bfe_i32 v178, v182, 18, 1
	v_bfi_b32 v138, v178, v138, s13
	v_bfe_i32 v178, v182, 19, 1
	v_bfi_b32 v139, v178, v139, s13
	v_bfe_i32 v178, v182, 20, 1
	v_bfi_b32 v140, v178, v140, s13
	v_bfe_i32 v178, v182, 21, 1
	v_bfi_b32 v141, v178, v141, s13
	v_bfe_i32 v178, v182, 22, 1
	v_bfi_b32 v142, v178, v142, s13
	v_bfe_i32 v178, v182, 23, 1
	v_bfi_b32 v143, v178, v143, s13
	s_nop 1
; #define LAS __attribute__((address_space(3)))
; __device__ __forceinline__ unsigned pk2(float lo, float hi) { return pg8::cvt_pk_bf16(lo, hi); }
; #define LDS_WAIT() asm volatile("s_waitcnt lgkmcnt(0)" ::: "memory")
; __device__ __forceinline__ s16x4 vtr(const LAS unsigned char* p) { return __builtin_bit_cast(s16x4, __builtin_amdgcn_ds_read_tr16_b64_v4i16((LAS s16x4*)p)); }
; __device__ __forceinline__ void dsa_unit(const bf16* QB, const int* SEL, bf16* AO, int b, int kvh, int t, LAS unsigned char* wl, int lane) {
;     ...
;     for (int g = 0; g < 4; ++g) {
;         float m = mx[g];
;         m = __builtin_fmaxf(m, __shfl_xor(m, 1)); m = __builtin_fmaxf(m, __shfl_xor(m, 2)); m = __builtin_fmaxf(m, __shfl_xor(m, 4)); m = __builtin_fmaxf(m, __shfl_xor(m, 8)); m = __builtin_fmaxf(m, __shfl_xor(m, 16));
;         float s = 0.f;
; #pragma unroll
;         for (int kb = 0; kb < 8; ++kb) { const float e = __builtin_amdgcn_exp2f(lg[kb][g] - m); lg[kb][g] = e; s += e; }
;         s += __shfl_xor(s, 1); s += __shfl_xor(s, 2); s += __shfl_xor(s, 4); s += __shfl_xor(s, 8); s += __shfl_xor(s, 16);
;         const float inv = 1.0f / s;
; #pragma unroll
;         for (int kb = 0; kb < 8; ++kb) if ((kb >> 2) == hi) pT[g * 256 + 32 * kb + n] = (bf16)(pk2(lg[kb][g] * inv, 0.f) & 0xffffu);
;     }
;     f32x4v o[8];
; #pragma unroll
;     for (int c = 0; c < 8; ++c) o[c] = (f32x4v){0.f, 0.f, 0.f, 0.f};
;     const LAS unsigned char* vtb = buf + (8 * kq + (l15 >> 2)) * 288 + (lane & 3) * 8;
;     LAS unsigned char* vdst = buf + r4 * 288 + c16 * 16;
;     const LAS bf16* pfp = pT + (l15 & 3) * 256 + 8 * kq;
; #pragma unroll
;     for (int ch = 0; ch < 8; ++ch) {
; #pragma unroll
;         for (int i = 0; i < 8; ++i) *(LAS bf16x8*)(vdst + (4 * i) * 288) = vr[ch % 3][i];
;         if (ch + 3 < 8) {
; #pragma unroll
;             for (int i = 0; i < 8; ++i) vr[ch % 3][i] = *(const bf16x8*)(vg + (size_t)il[32 * (ch + 3) + 4 * i + r4] * NBP);
;         }
;         const bf16x8 pf = *(const LAS bf16x8*)(pfp + 32 * ch);
;         LDS_WAIT();
; #pragma unroll
;         for (int c = 0; c < 8; ++c) {
;             const s16x4 lo = vtr(vtb + c * 32), hh = vtr(vtb + 4 * 288 + c * 32);
;             o[c] = __builtin_amdgcn_mfma_f32_16x16x32_bf16(pf, (bf16x8){lo[0], lo[1], lo[2], lo[3], hh[0], hh[1], hh[2], hh[3]}, o[c], 0, 0, 0);
;         }
;         LDS_WAIT();
;     }
.Ldsa_farB0:
	ds_read_b32 v174, v172 offset:8
	ds_read_b32 v182, v172 offset:12
	s_nop 1
	s_waitcnt lgkmcnt(5)
	v_mfma_f32_32x32x16_bf16 v[128:143], v[112:115], v[80:83], v[128:143]
	ds_read_b128 v[112:115], v168 offset:8832
	v_exp_f32_e32 v64, v64
	v_exp_f32_e32 v65, v65
	v_add_f32_e32 v173, v173, v64
	v_add_f32_e32 v173, v173, v65
	v_cvt_pk_bf16_f32 v64, v64, v65
	s_waitcnt lgkmcnt(5)
	v_mfma_f32_32x32x16_bf16 v[128:143], v[116:119], v[84:87], v[128:143]
	ds_read_b128 v[116:119], v168 offset:8864
	v_exp_f32_e32 v66, v66
	v_exp_f32_e32 v67, v67
	v_add_f32_e32 v173, v173, v66
	v_add_f32_e32 v173, v173, v67
	v_cvt_pk_bf16_f32 v65, v66, v67
	s_waitcnt lgkmcnt(5)
	v_mfma_f32_32x32x16_bf16 v[128:143], v[120:123], v[88:91], v[128:143]
	ds_read_b128 v[120:123], v168 offset:8896
	v_exp_f32_e32 v68, v68
	v_exp_f32_e32 v69, v69
	v_add_f32_e32 v173, v173, v68
	v_add_f32_e32 v173, v173, v69
	v_cvt_pk_bf16_f32 v66, v68, v69
	s_waitcnt lgkmcnt(5)
	v_mfma_f32_32x32x16_bf16 v[128:143], v[124:127], v[92:95], v[128:143]
	ds_read_b128 v[124:127], v168 offset:8928
	v_exp_f32_e32 v70, v70
	v_exp_f32_e32 v71, v71
	v_add_f32_e32 v173, v173, v70
	v_add_f32_e32 v173, v173, v71
	v_cvt_pk_bf16_f32 v67, v70, v71
	s_waitcnt lgkmcnt(3)
	v_mfma_f32_32x32x16_bf16 v[128:143], v[112:115], v[96:99], v[128:143]
	ds_read_b64_tr_b16 v[112:113], v169 offset:0
	ds_read_b64_tr_b16 v[114:115], v169 offset:1152
	v_exp_f32_e32 v72, v72
	v_exp_f32_e32 v73, v73
	v_add_f32_e32 v173, v173, v72
	v_add_f32_e32 v173, v173, v73
	v_cvt_pk_bf16_f32 v68, v72, v73
	s_waitcnt lgkmcnt(4)
	v_mfma_f32_32x32x16_bf16 v[128:143], v[116:119], v[100:103], v[128:143]
	ds_read_b64_tr_b16 v[116:117], v169 offset:64
	ds_read_b64_tr_b16 v[118:119], v169 offset:1216
	v_exp_f32_e32 v74, v74
	v_exp_f32_e32 v75, v75
	v_add_f32_e32 v173, v173, v74
	v_add_f32_e32 v173, v173, v75
	v_cvt_pk_bf16_f32 v69, v74, v75
	s_waitcnt lgkmcnt(5)
	v_mfma_f32_32x32x16_bf16 v[128:143], v[120:123], v[104:107], v[128:143]
	ds_read_b64_tr_b16 v[120:121], v169 offset:128
	ds_read_b64_tr_b16 v[122:123], v169 offset:1280
	v_exp_f32_e32 v76, v76
	v_exp_f32_e32 v77, v77
	v_add_f32_e32 v173, v173, v76
	v_add_f32_e32 v173, v173, v77
	v_cvt_pk_bf16_f32 v70, v76, v77
	s_waitcnt lgkmcnt(6)
	v_mfma_f32_32x32x16_bf16 v[128:143], v[124:127], v[108:111], v[128:143]
	ds_read_b64_tr_b16 v[124:125], v169 offset:192
	ds_read_b64_tr_b16 v[126:127], v169 offset:1344
	v_exp_f32_e32 v78, v78
	v_exp_f32_e32 v79, v79
	v_add_f32_e32 v173, v173, v78
	v_add_f32_e32 v173, v173, v79
	v_cvt_pk_bf16_f32 v71, v78, v79
	s_waitcnt lgkmcnt(6)
	v_mfma_f32_32x32x16_bf16 v[0:15], v[64:67], v[112:115], v[0:15]
	ds_read_b64_tr_b16 v[112:113], v169 offset:4608
	ds_read_b64_tr_b16 v[114:115], v169 offset:5760
	s_waitcnt vmcnt(4)
	ds_write_b128 v170, v[188:191]
	v_exp_f32_e32 v128, v128
	v_exp_f32_e32 v129, v129
	v_add_f32_e32 v173, v173, v128
	v_add_f32_e32 v173, v173, v129
	v_cvt_pk_bf16_f32 v128, v128, v129
	s_waitcnt lgkmcnt(7)
	v_mfma_f32_32x32x16_bf16 v[16:31], v[64:67], v[116:119], v[16:31]
	ds_read_b64_tr_b16 v[116:117], v169 offset:4672
	ds_read_b64_tr_b16 v[118:119], v169 offset:5824
	ds_write_b128 v171, v[192:195]
	v_exp_f32_e32 v130, v130
	v_exp_f32_e32 v131, v131
	v_add_f32_e32 v173, v173, v130
	v_add_f32_e32 v173, v173, v131
	v_cvt_pk_bf16_f32 v129, v130, v131
	s_waitcnt lgkmcnt(8)
	v_mfma_f32_32x32x16_bf16 v[32:47], v[64:67], v[120:123], v[32:47]
	ds_read_b64_tr_b16 v[120:121], v169 offset:4736
	ds_read_b64_tr_b16 v[122:123], v169 offset:5888
	ds_write_b128 v170, v[196:199] offset:8704
	v_exp_f32_e32 v132, v132
	v_exp_f32_e32 v133, v133
	v_add_f32_e32 v173, v173, v132
	v_add_f32_e32 v173, v173, v133
	v_cvt_pk_bf16_f32 v130, v132, v133
	s_waitcnt lgkmcnt(9)
	v_mfma_f32_32x32x16_bf16 v[48:63], v[64:67], v[124:127], v[48:63]
	ds_read_b64_tr_b16 v[124:125], v169 offset:4800
	ds_read_b64_tr_b16 v[126:127], v169 offset:5952
	ds_write_b128 v171, v[200:203] offset:9216
	v_exp_f32_e32 v134, v134
	v_exp_f32_e32 v135, v135
	v_add_f32_e32 v173, v173, v134
	v_add_f32_e32 v173, v173, v135
	v_cvt_pk_bf16_f32 v131, v134, v135
	s_waitcnt lgkmcnt(10)
	v_mfma_f32_32x32x16_bf16 v[0:15], v[68:71], v[112:115], v[0:15]
	ds_read_b64_tr_b16 v[112:113], v169 offset:9216
	ds_read_b64_tr_b16 v[114:115], v169 offset:10368
	s_nop 0
	v_exp_f32_e32 v136, v136
	v_exp_f32_e32 v137, v137
	v_add_f32_e32 v173, v173, v136
	v_add_f32_e32 v173, v173, v137
	v_cvt_pk_bf16_f32 v132, v136, v137
	s_waitcnt lgkmcnt(9)
	v_mfma_f32_32x32x16_bf16 v[16:31], v[68:71], v[116:119], v[16:31]
	ds_read_b64_tr_b16 v[116:117], v169 offset:9280
	ds_read_b64_tr_b16 v[118:119], v169 offset:10432
	s_nop 0
	v_exp_f32_e32 v138, v138
	v_exp_f32_e32 v139, v139
	v_add_f32_e32 v173, v173, v138
	v_add_f32_e32 v173, v173, v139
	v_cvt_pk_bf16_f32 v133, v138, v139
	s_waitcnt lgkmcnt(8)
	v_mfma_f32_32x32x16_bf16 v[32:47], v[68:71], v[120:123], v[32:47]
	ds_read_b64_tr_b16 v[120:121], v169 offset:9344
	ds_read_b64_tr_b16 v[122:123], v169 offset:10496
	s_nop 0
	v_exp_f32_e32 v140, v140
	v_exp_f32_e32 v141, v141
	v_add_f32_e32 v173, v173, v140
	v_add_f32_e32 v173, v173, v141
	v_cvt_pk_bf16_f32 v134, v140, v141
	s_waitcnt lgkmcnt(7)
	v_mfma_f32_32x32x16_bf16 v[48:63], v[68:71], v[124:127], v[48:63]
	ds_read_b64_tr_b16 v[124:125], v169 offset:9408
	ds_read_b64_tr_b16 v[126:127], v169 offset:10560
	s_nop 0
	v_exp_f32_e32 v142, v142
	v_exp_f32_e32 v143, v143
	v_add_f32_e32 v173, v173, v142
	v_add_f32_e32 v173, v173, v143
	v_cvt_pk_bf16_f32 v135, v142, v143
	v_lshrrev_b32_e32 v174, v175, v174
	s_waitcnt lgkmcnt(6)
; #define LAS __attribute__((address_space(3)))
; #define LDS_WAIT() asm volatile("s_waitcnt lgkmcnt(0)" ::: "memory")
; __device__ __forceinline__ s16x4 vtr(const LAS unsigned char* p) { return __builtin_bit_cast(s16x4, __builtin_amdgcn_ds_read_tr16_b64_v4i16((LAS s16x4*)p)); }
; __device__ __forceinline__ void dsa_unit(const bf16* QB, const int* SEL, bf16* AO, int b, int kvh, int t, LAS unsigned char* wl, int lane) {
;     ...
;     for (int kb = 0; kb < 8; ++kb) {
; #pragma unroll
;         for (int i = 0; i < 8; ++i) *(LAS bf16x8*)(kdst + (4 * i) * 272) = kr[kb % 3][i];
;         if (kb + 3 < 8) {
; #pragma unroll
;             for (int i = 0; i < 8; ++i) kr[kb % 3][i] = *(const bf16x8*)(kg + (size_t)il[32 * (kb + 3) + 4 * i + r4] * NBP);
;         }
;         LDS_WAIT();
;         f32x4v a0 = {0.f, 0.f, 0.f, 0.f}, a1 = {0.f, 0.f, 0.f, 0.f};
; #pragma unroll
;         for (int ks = 0; ks < 4; ++ks) { const bf16x8 b0 = *(const LAS bf16x8*)(kfb + 64 * ks), b1 = *(const LAS bf16x8*)(kfb + 16 * 272 + 64 * ks);
;             a0 = __builtin_amdgcn_mfma_f32_16x16x32_bf16(qf[ks], b0, a0, 0, 0, 0); a1 = __builtin_amdgcn_mfma_f32_16x16x32_bf16(qf[ks], b1, a1, 0, 0, 0); }
;         LDS_WAIT();
;         const int bk = t5_bucket(sidx[kb] - t);
;         const bool valid = (32 * kb + n) < nsel;
; #pragma unroll
;         for (int g = 0; g < 4; ++g) { const float raw = upper ? a1[g] : a0[g]; const float v = valid ? raw + bl[g * 32 + bk] : -__builtin_inff(); lg[kb][g] = v; mx[g] = __builtin_fmaxf(mx[g], v); }
;     }
;     ...
;     for (int ch = 0; ch < 8; ++ch) {
; #pragma unroll
;         for (int i = 0; i < 8; ++i) *(LAS bf16x8*)(vdst + (4 * i) * 288) = vr[ch % 3][i];
;         if (ch + 3 < 8) {
; #pragma unroll
;             for (int i = 0; i < 8; ++i) vr[ch % 3][i] = *(const bf16x8*)(vg + (size_t)il[32 * (ch + 3) + 4 * i + r4] * NBP);
;         }
;         const bf16x8 pf = *(const LAS bf16x8*)(pfp + 32 * ch);
;         LDS_WAIT();
; #pragma unroll
;         for (int c = 0; c < 8; ++c) {
;             const s16x4 lo = vtr(vtb + c * 32), hh = vtr(vtb + 4 * 288 + c * 32);
;             o[c] = __builtin_amdgcn_mfma_f32_16x16x32_bf16(pf, (bf16x8){lo[0], lo[1], lo[2], lo[3], hh[0], hh[1], hh[2], hh[3]}, o[c], 0, 0, 0);
;         }
;         LDS_WAIT();
;     }
	v_mfma_f32_32x32x16_bf16 v[0:15], v[128:131], v[112:115], v[0:15]
	ds_read_b64_tr_b16 v[112:113], v169 offset:13824
	ds_read_b64_tr_b16 v[114:115], v169 offset:14976
	v_bfe_i32 v178, v174, 0, 1
	v_bfi_b32 v64, v178, v176, s13
	v_bfe_i32 v179, v174, 1, 1
	v_bfi_b32 v65, v179, v176, s13
	s_waitcnt lgkmcnt(6)
	v_mfma_f32_32x32x16_bf16 v[16:31], v[128:131], v[116:119], v[16:31]
	ds_read_b64_tr_b16 v[116:117], v169 offset:13888
	ds_read_b64_tr_b16 v[118:119], v169 offset:15040
	v_bfe_i32 v178, v174, 2, 1
	v_bfi_b32 v66, v178, v176, s13
	v_bfe_i32 v179, v174, 3, 1
	v_bfi_b32 v67, v179, v176, s13
	s_waitcnt lgkmcnt(6)
	v_mfma_f32_32x32x16_bf16 v[32:47], v[128:131], v[120:123], v[32:47]
	ds_read_b64_tr_b16 v[120:121], v169 offset:13952
	ds_read_b64_tr_b16 v[122:123], v169 offset:15104
	v_bfe_i32 v178, v174, 4, 1
	v_bfi_b32 v68, v178, v176, s13
	v_bfe_i32 v179, v174, 5, 1
	v_bfi_b32 v69, v179, v176, s13
	s_waitcnt lgkmcnt(6)
	v_mfma_f32_32x32x16_bf16 v[48:63], v[128:131], v[124:127], v[48:63]
	ds_read_b64_tr_b16 v[124:125], v169 offset:14016
	ds_read_b64_tr_b16 v[126:127], v169 offset:15168
	v_bfe_i32 v178, v174, 6, 1
	v_bfi_b32 v70, v178, v176, s13
	v_bfe_i32 v179, v174, 7, 1
	v_bfi_b32 v71, v179, v176, s13
	s_waitcnt lgkmcnt(6)
	v_mfma_f32_32x32x16_bf16 v[0:15], v[132:135], v[112:115], v[0:15]
	v_bfe_i32 v178, v174, 16, 1
	v_bfi_b32 v72, v178, v176, s13
	v_bfe_i32 v179, v174, 17, 1
	v_bfi_b32 v73, v179, v176, s13
	s_waitcnt lgkmcnt(4)
	v_mfma_f32_32x32x16_bf16 v[16:31], v[132:135], v[116:119], v[16:31]
	v_bfe_i32 v178, v174, 18, 1
	v_bfi_b32 v74, v178, v176, s13
	v_bfe_i32 v179, v174, 19, 1
	v_bfi_b32 v75, v179, v176, s13
	s_waitcnt lgkmcnt(2)
	v_mfma_f32_32x32x16_bf16 v[32:47], v[132:135], v[120:123], v[32:47]
	v_bfe_i32 v178, v174, 20, 1
	v_bfi_b32 v76, v178, v176, s13
	v_bfe_i32 v179, v174, 21, 1
	v_bfi_b32 v77, v179, v176, s13
	s_waitcnt lgkmcnt(0)
	v_mfma_f32_32x32x16_bf16 v[48:63], v[132:135], v[124:127], v[48:63]
	v_bfe_i32 v178, v174, 22, 1
	v_bfi_b32 v78, v178, v176, s13
	v_bfe_i32 v179, v174, 23, 1
	v_bfi_b32 v79, v179, v176, s13
	s_waitcnt lgkmcnt(0)
	s_barrier
	s_mov_b32 s25, s10
	s_mov_b32 s10, s11
	s_mov_b32 s11, s25
	v_add_u32_e32 v172, 8, v172
	s_mov_b32 s9, s24
	s_cmp_lt_u32 s9, s8
	s_cbranch_scc0 .Ldsa_exit
	v_add_u32_e32 v168, s10, v164
	ds_read_b128 v[112:115], v168 offset:0
	ds_read_b128 v[116:119], v168 offset:32
	ds_read_b128 v[120:123], v168 offset:64
	ds_read_b128 v[124:127], v168 offset:96
	v_add_u32_e32 v169, s10, v165
	v_add_u32_e32 v170, s11, v166
	v_add_u32_e32 v171, s11, v167
	s_add_u32 s24, s9, 1
	s_lshl_b32 s20, s9, 6
	s_add_u32 s27, s20, 32
	v_lshrrev_b32_e32 v182, v175, v182
	s_cmp_le_i32 s20, s19
	s_cbranch_scc1 .Ldsa_farA1
	s_lshl_b32 s26, s20, 2
	v_add_u32_e32 v179, s26, v177
	ds_read_b32 v64, v179 offset:0
	ds_read_b32 v65, v179 offset:4
	ds_read_b32 v66, v179 offset:8
	ds_read_b32 v67, v179 offset:12
	ds_read_b32 v68, v179 offset:16
	ds_read_b32 v69, v179 offset:20
	ds_read_b32 v70, v179 offset:24
	ds_read_b32 v71, v179 offset:28
	ds_read_b32 v72, v179 offset:64
	ds_read_b32 v73, v179 offset:68
	ds_read_b32 v74, v179 offset:72
	ds_read_b32 v75, v179 offset:76
	ds_read_b32 v76, v179 offset:80
	ds_read_b32 v77, v179 offset:84
	ds_read_b32 v78, v179 offset:88
	ds_read_b32 v79, v179 offset:92
	s_waitcnt lgkmcnt(0)
	v_bfe_i32 v178, v174, 0, 1
	v_bfi_b32 v64, v178, v64, s13
	v_bfe_i32 v178, v174, 1, 1
	v_bfi_b32 v65, v178, v65, s13
	v_bfe_i32 v178, v174, 2, 1
	v_bfi_b32 v66, v178, v66, s13
	v_bfe_i32 v178, v174, 3, 1
	v_bfi_b32 v67, v178, v67, s13
	v_bfe_i32 v178, v174, 4, 1
	v_bfi_b32 v68, v178, v68, s13
	v_bfe_i32 v178, v174, 5, 1
	v_bfi_b32 v69, v178, v69, s13
	v_bfe_i32 v178, v174, 6, 1
	v_bfi_b32 v70, v178, v70, s13
	v_bfe_i32 v178, v174, 7, 1
	v_bfi_b32 v71, v178, v71, s13
	v_bfe_i32 v178, v174, 16, 1
	v_bfi_b32 v72, v178, v72, s13
	v_bfe_i32 v178, v174, 17, 1
	v_bfi_b32 v73, v178, v73, s13
	v_bfe_i32 v178, v174, 18, 1
	v_bfi_b32 v74, v178, v74, s13
	v_bfe_i32 v178, v174, 19, 1
	v_bfi_b32 v75, v178, v75, s13
	v_bfe_i32 v178, v174, 20, 1
	v_bfi_b32 v76, v178, v76, s13
	v_bfe_i32 v178, v174, 21, 1
	v_bfi_b32 v77, v178, v77, s13
	v_bfe_i32 v178, v174, 22, 1
	v_bfi_b32 v78, v178, v78, s13
	v_bfe_i32 v178, v174, 23, 1
	v_bfi_b32 v79, v178, v79, s13
	s_nop 1
; #define LAS __attribute__((address_space(3)))
; #define LDS_WAIT() asm volatile("s_waitcnt lgkmcnt(0)" ::: "memory")
; __device__ __forceinline__ void dsa_unit(const bf16* QB, const int* SEL, bf16* AO, int b, int kvh, int t, LAS unsigned char* wl, int lane) {
;     ...
;     for (int kb = 0; kb < 8; ++kb) {
; #pragma unroll
;         for (int i = 0; i < 8; ++i) *(LAS bf16x8*)(kdst + (4 * i) * 272) = kr[kb % 3][i];
;         if (kb + 3 < 8) {
; #pragma unroll
;             for (int i = 0; i < 8; ++i) kr[kb % 3][i] = *(const bf16x8*)(kg + (size_t)il[32 * (kb + 3) + 4 * i + r4] * NBP);
;         }
;         LDS_WAIT();
;         f32x4v a0 = {0.f, 0.f, 0.f, 0.f}, a1 = {0.f, 0.f, 0.f, 0.f};
; #pragma unroll
;         for (int ks = 0; ks < 4; ++ks) { const bf16x8 b0 = *(const LAS bf16x8*)(kfb + 64 * ks), b1 = *(const LAS bf16x8*)(kfb + 16 * 272 + 64 * ks);
;             a0 = __builtin_amdgcn_mfma_f32_16x16x32_bf16(qf[ks], b0, a0, 0, 0, 0); a1 = __builtin_amdgcn_mfma_f32_16x16x32_bf16(qf[ks], b1, a1, 0, 0, 0); }
;         LDS_WAIT();
;         const int bk = t5_bucket(sidx[kb] - t);
;         const bool valid = (32 * kb + n) < nsel;
; #pragma unroll
;         for (int g = 0; g < 4; ++g) { const float raw = upper ? a1[g] : a0[g]; const float v = valid ? raw + bl[g * 32 + bk] : -__builtin_inff(); lg[kb][g] = v; mx[g] = __builtin_fmaxf(mx[g], v); }
;     }
.Ldsa_farA1:
	s_waitcnt lgkmcnt(3)
	v_mfma_f32_32x32x16_bf16 v[64:79], v[112:115], v[80:83], v[64:79]
	ds_read_b128 v[112:115], v168 offset:128
	v_bfe_i32 v178, v182, 0, 1
	v_bfi_b32 v128, v178, v176, s13
	v_bfe_i32 v179, v182, 1, 1
	v_bfi_b32 v129, v179, v176, s13
	s_waitcnt lgkmcnt(3)
	v_mfma_f32_32x32x16_bf16 v[64:79], v[116:119], v[84:87], v[64:79]
	ds_read_b128 v[116:119], v168 offset:160
	v_bfe_i32 v178, v182, 2, 1
	v_bfi_b32 v130, v178, v176, s13
	v_bfe_i32 v179, v182, 3, 1
	v_bfi_b32 v131, v179, v176, s13
	global_load_dwordx4 v[188:191], v[160:161], off
	s_waitcnt lgkmcnt(3)
	v_mfma_f32_32x32x16_bf16 v[64:79], v[120:123], v[88:91], v[64:79]
	ds_read_b128 v[120:123], v168 offset:192
	v_bfe_i32 v178, v182, 4, 1
	v_bfi_b32 v132, v178, v176, s13
	v_bfe_i32 v179, v182, 5, 1
	v_bfi_b32 v133, v179, v176, s13
	global_load_dwordx4 v[192:195], v[160:161], off offset:1024
	s_waitcnt lgkmcnt(3)
	v_mfma_f32_32x32x16_bf16 v[64:79], v[124:127], v[92:95], v[64:79]
	ds_read_b128 v[124:127], v168 offset:224
	v_bfe_i32 v178, v182, 6, 1
	v_bfi_b32 v134, v178, v176, s13
	v_bfe_i32 v179, v182, 7, 1
	v_bfi_b32 v135, v179, v176, s13
	global_load_dwordx4 v[196:199], v[162:163], off
	s_waitcnt lgkmcnt(3)
	v_mfma_f32_32x32x16_bf16 v[64:79], v[112:115], v[96:99], v[64:79]
	ds_read_b128 v[112:115], v168 offset:8704
	v_bfe_i32 v178, v182, 16, 1
	v_bfi_b32 v136, v178, v176, s13
	v_bfe_i32 v179, v182, 17, 1
	v_bfi_b32 v137, v179, v176, s13
	global_load_dwordx4 v[200:203], v[162:163], off offset:1024
	s_waitcnt lgkmcnt(3)
	v_mfma_f32_32x32x16_bf16 v[64:79], v[116:119], v[100:103], v[64:79]
	ds_read_b128 v[116:119], v168 offset:8736
	v_bfe_i32 v178, v182, 18, 1
	v_bfi_b32 v138, v178, v176, s13
	v_bfe_i32 v179, v182, 19, 1
	v_bfi_b32 v139, v179, v176, s13
	s_add_u32 s40, s9, 3
	s_cmp_lt_u32 s40, s8
	s_cselect_b32 s40, s16, 0
	v_lshl_add_u64 v[160:161], v[160:161], 0, s[40:41]
	v_lshl_add_u64 v[162:163], v[162:163], 0, s[40:41]
	s_waitcnt lgkmcnt(3)
	v_mfma_f32_32x32x16_bf16 v[64:79], v[120:123], v[104:107], v[64:79]
	ds_read_b128 v[120:123], v168 offset:8768
	v_bfe_i32 v178, v182, 20, 1
	v_bfi_b32 v140, v178, v176, s13
	v_bfe_i32 v179, v182, 21, 1
	v_bfi_b32 v141, v179, v176, s13
	s_waitcnt lgkmcnt(3)
	v_mfma_f32_32x32x16_bf16 v[64:79], v[124:127], v[108:111], v[64:79]
	ds_read_b128 v[124:127], v168 offset:8800
	v_bfe_i32 v178, v182, 22, 1
	v_bfi_b32 v142, v178, v176, s13
	v_bfe_i32 v179, v182, 23, 1
	v_bfi_b32 v143, v179, v176, s13
	s_cmp_le_i32 s27, s19
	s_cbranch_scc1 .Ldsa_farB1
	s_lshl_b32 s26, s27, 2
	v_add_u32_e32 v179, s26, v177
	ds_read_b32 v128, v179 offset:0
	ds_read_b32 v129, v179 offset:4
	ds_read_b32 v130, v179 offset:8
	ds_read_b32 v131, v179 offset:12
	ds_read_b32 v132, v179 offset:16
	ds_read_b32 v133, v179 offset:20
	ds_read_b32 v134, v179 offset:24
	ds_read_b32 v135, v179 offset:28
	ds_read_b32 v136, v179 offset:64
	ds_read_b32 v137, v179 offset:68
	ds_read_b32 v138, v179 offset:72
	ds_read_b32 v139, v179 offset:76
	ds_read_b32 v140, v179 offset:80
	ds_read_b32 v141, v179 offset:84
	ds_read_b32 v142, v179 offset:88
	ds_read_b32 v143, v179 offset:92
	s_waitcnt lgkmcnt(0)
	v_bfe_i32 v178, v182, 0, 1
	v_bfi_b32 v128, v178, v128, s13
	v_bfe_i32 v178, v182, 1, 1
	v_bfi_b32 v129, v178, v129, s13
	v_bfe_i32 v178, v182, 2, 1
	v_bfi_b32 v130, v178, v130, s13
	v_bfe_i32 v178, v182, 3, 1
	v_bfi_b32 v131, v178, v131, s13
	v_bfe_i32 v178, v182, 4, 1
	v_bfi_b32 v132, v178, v132, s13
	v_bfe_i32 v178, v182, 5, 1
	v_bfi_b32 v133, v178, v133, s13
	v_bfe_i32 v178, v182, 6, 1
	v_bfi_b32 v134, v178, v134, s13
	v_bfe_i32 v178, v182, 7, 1
	v_bfi_b32 v135, v178, v135, s13
	v_bfe_i32 v178, v182, 16, 1
	v_bfi_b32 v136, v178, v136, s13
	v_bfe_i32 v178, v182, 17, 1
	v_bfi_b32 v137, v178, v137, s13
	v_bfe_i32 v178, v182, 18, 1
	v_bfi_b32 v138, v178, v138, s13
	v_bfe_i32 v178, v182, 19, 1
	v_bfi_b32 v139, v178, v139, s13
	v_bfe_i32 v178, v182, 20, 1
	v_bfi_b32 v140, v178, v140, s13
	v_bfe_i32 v178, v182, 21, 1
	v_bfi_b32 v141, v178, v141, s13
	v_bfe_i32 v178, v182, 22, 1
	v_bfi_b32 v142, v178, v142, s13
	v_bfe_i32 v178, v182, 23, 1
	v_bfi_b32 v143, v178, v143, s13
	s_nop 1
.Ldsa_farB1:
	ds_read_b32 v174, v172 offset:8
	ds_read_b32 v182, v172 offset:12
	s_nop 1
	s_waitcnt lgkmcnt(5)
	v_mfma_f32_32x32x16_bf16 v[128:143], v[112:115], v[80:83], v[128:143]
	ds_read_b128 v[112:115], v168 offset:8832
	v_exp_f32_e32 v64, v64
	v_exp_f32_e32 v65, v65
	v_add_f32_e32 v173, v173, v64
	v_add_f32_e32 v173, v173, v65
	v_cvt_pk_bf16_f32 v64, v64, v65
	s_waitcnt lgkmcnt(5)
	v_mfma_f32_32x32x16_bf16 v[128:143], v[116:119], v[84:87], v[128:143]
	ds_read_b128 v[116:119], v168 offset:8864
	v_exp_f32_e32 v66, v66
	v_exp_f32_e32 v67, v67
	v_add_f32_e32 v173, v173, v66
	v_add_f32_e32 v173, v173, v67
	v_cvt_pk_bf16_f32 v65, v66, v67
	s_waitcnt lgkmcnt(5)
	v_mfma_f32_32x32x16_bf16 v[128:143], v[120:123], v[88:91], v[128:143]
	ds_read_b128 v[120:123], v168 offset:8896
	v_exp_f32_e32 v68, v68
	v_exp_f32_e32 v69, v69
	v_add_f32_e32 v173, v173, v68
	v_add_f32_e32 v173, v173, v69
	v_cvt_pk_bf16_f32 v66, v68, v69
	s_waitcnt lgkmcnt(5)
	v_mfma_f32_32x32x16_bf16 v[128:143], v[124:127], v[92:95], v[128:143]
	ds_read_b128 v[124:127], v168 offset:8928
	v_exp_f32_e32 v70, v70
	v_exp_f32_e32 v71, v71
	v_add_f32_e32 v173, v173, v70
	v_add_f32_e32 v173, v173, v71
	v_cvt_pk_bf16_f32 v67, v70, v71
	s_waitcnt lgkmcnt(3)
	v_mfma_f32_32x32x16_bf16 v[128:143], v[112:115], v[96:99], v[128:143]
	ds_read_b64_tr_b16 v[112:113], v169 offset:0
	ds_read_b64_tr_b16 v[114:115], v169 offset:1152
	v_exp_f32_e32 v72, v72
	v_exp_f32_e32 v73, v73
	v_add_f32_e32 v173, v173, v72
	v_add_f32_e32 v173, v173, v73
	v_cvt_pk_bf16_f32 v68, v72, v73
	s_waitcnt lgkmcnt(4)
; #define LAS __attribute__((address_space(3)))
; __device__ __forceinline__ unsigned pk2(float lo, float hi) { return pg8::cvt_pk_bf16(lo, hi); }
; #define LDS_WAIT() asm volatile("s_waitcnt lgkmcnt(0)" ::: "memory")
; __device__ __forceinline__ s16x4 vtr(const LAS unsigned char* p) { return __builtin_bit_cast(s16x4, __builtin_amdgcn_ds_read_tr16_b64_v4i16((LAS s16x4*)p)); }
; __device__ __forceinline__ void dsa_unit(const bf16* QB, const int* SEL, bf16* AO, int b, int kvh, int t, LAS unsigned char* wl, int lane) {
;     ...
;     for (int g = 0; g < 4; ++g) {
;         float m = mx[g];
;         m = __builtin_fmaxf(m, __shfl_xor(m, 1)); m = __builtin_fmaxf(m, __shfl_xor(m, 2)); m = __builtin_fmaxf(m, __shfl_xor(m, 4)); m = __builtin_fmaxf(m, __shfl_xor(m, 8)); m = __builtin_fmaxf(m, __shfl_xor(m, 16));
;         float s = 0.f;
; #pragma unroll
;         for (int kb = 0; kb < 8; ++kb) { const float e = __builtin_amdgcn_exp2f(lg[kb][g] - m); lg[kb][g] = e; s += e; }
;         s += __shfl_xor(s, 1); s += __shfl_xor(s, 2); s += __shfl_xor(s, 4); s += __shfl_xor(s, 8); s += __shfl_xor(s, 16);
;         const float inv = 1.0f / s;
; #pragma unroll
;         for (int kb = 0; kb < 8; ++kb) if ((kb >> 2) == hi) pT[g * 256 + 32 * kb + n] = (bf16)(pk2(lg[kb][g] * inv, 0.f) & 0xffffu);
;     }
;     f32x4v o[8];
; #pragma unroll
;     for (int c = 0; c < 8; ++c) o[c] = (f32x4v){0.f, 0.f, 0.f, 0.f};
;     const LAS unsigned char* vtb = buf + (8 * kq + (l15 >> 2)) * 288 + (lane & 3) * 8;
;     LAS unsigned char* vdst = buf + r4 * 288 + c16 * 16;
;     const LAS bf16* pfp = pT + (l15 & 3) * 256 + 8 * kq;
; #pragma unroll
;     for (int ch = 0; ch < 8; ++ch) {
; #pragma unroll
;         for (int i = 0; i < 8; ++i) *(LAS bf16x8*)(vdst + (4 * i) * 288) = vr[ch % 3][i];
;         if (ch + 3 < 8) {
; #pragma unroll
;             for (int i = 0; i < 8; ++i) vr[ch % 3][i] = *(const bf16x8*)(vg + (size_t)il[32 * (ch + 3) + 4 * i + r4] * NBP);
;         }
;         const bf16x8 pf = *(const LAS bf16x8*)(pfp + 32 * ch);
;         LDS_WAIT();
; #pragma unroll
;         for (int c = 0; c < 8; ++c) {
;             const s16x4 lo = vtr(vtb + c * 32), hh = vtr(vtb + 4 * 288 + c * 32);
;             o[c] = __builtin_amdgcn_mfma_f32_16x16x32_bf16(pf, (bf16x8){lo[0], lo[1], lo[2], lo[3], hh[0], hh[1], hh[2], hh[3]}, o[c], 0, 0, 0);
;         }
;         LDS_WAIT();
;     }
	v_mfma_f32_32x32x16_bf16 v[128:143], v[116:119], v[100:103], v[128:143]
	ds_read_b64_tr_b16 v[116:117], v169 offset:64
	ds_read_b64_tr_b16 v[118:119], v169 offset:1216
	v_exp_f32_e32 v74, v74
	v_exp_f32_e32 v75, v75
	v_add_f32_e32 v173, v173, v74
	v_add_f32_e32 v173, v173, v75
	v_cvt_pk_bf16_f32 v69, v74, v75
	s_waitcnt lgkmcnt(5)
	v_mfma_f32_32x32x16_bf16 v[128:143], v[120:123], v[104:107], v[128:143]
	ds_read_b64_tr_b16 v[120:121], v169 offset:128
	ds_read_b64_tr_b16 v[122:123], v169 offset:1280
	v_exp_f32_e32 v76, v76
	v_exp_f32_e32 v77, v77
	v_add_f32_e32 v173, v173, v76
	v_add_f32_e32 v173, v173, v77
	v_cvt_pk_bf16_f32 v70, v76, v77
	s_waitcnt lgkmcnt(6)
	v_mfma_f32_32x32x16_bf16 v[128:143], v[124:127], v[108:111], v[128:143]
	ds_read_b64_tr_b16 v[124:125], v169 offset:192
	ds_read_b64_tr_b16 v[126:127], v169 offset:1344
	v_exp_f32_e32 v78, v78
	v_exp_f32_e32 v79, v79
	v_add_f32_e32 v173, v173, v78
	v_add_f32_e32 v173, v173, v79
	v_cvt_pk_bf16_f32 v71, v78, v79
	s_waitcnt lgkmcnt(6)
	v_mfma_f32_32x32x16_bf16 v[0:15], v[64:67], v[112:115], v[0:15]
	ds_read_b64_tr_b16 v[112:113], v169 offset:4608
	ds_read_b64_tr_b16 v[114:115], v169 offset:5760
	s_waitcnt vmcnt(4)
	ds_write_b128 v170, v[144:147]
	v_exp_f32_e32 v128, v128
	v_exp_f32_e32 v129, v129
	v_add_f32_e32 v173, v173, v128
	v_add_f32_e32 v173, v173, v129
	v_cvt_pk_bf16_f32 v128, v128, v129
	s_waitcnt lgkmcnt(7)
	v_mfma_f32_32x32x16_bf16 v[16:31], v[64:67], v[116:119], v[16:31]
	ds_read_b64_tr_b16 v[116:117], v169 offset:4672
	ds_read_b64_tr_b16 v[118:119], v169 offset:5824
	ds_write_b128 v171, v[148:151]
	v_exp_f32_e32 v130, v130
	v_exp_f32_e32 v131, v131
	v_add_f32_e32 v173, v173, v130
	v_add_f32_e32 v173, v173, v131
	v_cvt_pk_bf16_f32 v129, v130, v131
	s_waitcnt lgkmcnt(8)
	v_mfma_f32_32x32x16_bf16 v[32:47], v[64:67], v[120:123], v[32:47]
	ds_read_b64_tr_b16 v[120:121], v169 offset:4736
	ds_read_b64_tr_b16 v[122:123], v169 offset:5888
	ds_write_b128 v170, v[152:155] offset:8704
	v_exp_f32_e32 v132, v132
	v_exp_f32_e32 v133, v133
	v_add_f32_e32 v173, v173, v132
	v_add_f32_e32 v173, v173, v133
	v_cvt_pk_bf16_f32 v130, v132, v133
	s_waitcnt lgkmcnt(9)
	v_mfma_f32_32x32x16_bf16 v[48:63], v[64:67], v[124:127], v[48:63]
	ds_read_b64_tr_b16 v[124:125], v169 offset:4800
	ds_read_b64_tr_b16 v[126:127], v169 offset:5952
	ds_write_b128 v171, v[156:159] offset:9216
	v_exp_f32_e32 v134, v134
	v_exp_f32_e32 v135, v135
	v_add_f32_e32 v173, v173, v134
	v_add_f32_e32 v173, v173, v135
	v_cvt_pk_bf16_f32 v131, v134, v135
	s_waitcnt lgkmcnt(10)
	v_mfma_f32_32x32x16_bf16 v[0:15], v[68:71], v[112:115], v[0:15]
	ds_read_b64_tr_b16 v[112:113], v169 offset:9216
	ds_read_b64_tr_b16 v[114:115], v169 offset:10368
	s_nop 0
	v_exp_f32_e32 v136, v136
	v_exp_f32_e32 v137, v137
	v_add_f32_e32 v173, v173, v136
	v_add_f32_e32 v173, v173, v137
	v_cvt_pk_bf16_f32 v132, v136, v137
	s_waitcnt lgkmcnt(9)
	v_mfma_f32_32x32x16_bf16 v[16:31], v[68:71], v[116:119], v[16:31]
	ds_read_b64_tr_b16 v[116:117], v169 offset:9280
	ds_read_b64_tr_b16 v[118:119], v169 offset:10432
	s_nop 0
	v_exp_f32_e32 v138, v138
	v_exp_f32_e32 v139, v139
	v_add_f32_e32 v173, v173, v138
	v_add_f32_e32 v173, v173, v139
	v_cvt_pk_bf16_f32 v133, v138, v139
	s_waitcnt lgkmcnt(8)
	v_mfma_f32_32x32x16_bf16 v[32:47], v[68:71], v[120:123], v[32:47]
	ds_read_b64_tr_b16 v[120:121], v169 offset:9344
	ds_read_b64_tr_b16 v[122:123], v169 offset:10496
	s_nop 0
	v_exp_f32_e32 v140, v140
	v_exp_f32_e32 v141, v141
	v_add_f32_e32 v173, v173, v140
	v_add_f32_e32 v173, v173, v141
	v_cvt_pk_bf16_f32 v134, v140, v141
	s_waitcnt lgkmcnt(7)
	v_mfma_f32_32x32x16_bf16 v[48:63], v[68:71], v[124:127], v[48:63]
	ds_read_b64_tr_b16 v[124:125], v169 offset:9408
	ds_read_b64_tr_b16 v[126:127], v169 offset:10560
	s_nop 0
	v_exp_f32_e32 v142, v142
	v_exp_f32_e32 v143, v143
	v_add_f32_e32 v173, v173, v142
	v_add_f32_e32 v173, v173, v143
	v_cvt_pk_bf16_f32 v135, v142, v143
	v_lshrrev_b32_e32 v174, v175, v174
	s_waitcnt lgkmcnt(6)
	v_mfma_f32_32x32x16_bf16 v[0:15], v[128:131], v[112:115], v[0:15]
	ds_read_b64_tr_b16 v[112:113], v169 offset:13824
	ds_read_b64_tr_b16 v[114:115], v169 offset:14976
	v_bfe_i32 v178, v174, 0, 1
	v_bfi_b32 v64, v178, v176, s13
	v_bfe_i32 v179, v174, 1, 1
	v_bfi_b32 v65, v179, v176, s13
	s_waitcnt lgkmcnt(6)
	v_mfma_f32_32x32x16_bf16 v[16:31], v[128:131], v[116:119], v[16:31]
	ds_read_b64_tr_b16 v[116:117], v169 offset:13888
	ds_read_b64_tr_b16 v[118:119], v169 offset:15040
	v_bfe_i32 v178, v174, 2, 1
	v_bfi_b32 v66, v178, v176, s13
	v_bfe_i32 v179, v174, 3, 1
	v_bfi_b32 v67, v179, v176, s13
	s_waitcnt lgkmcnt(6)
	v_mfma_f32_32x32x16_bf16 v[32:47], v[128:131], v[120:123], v[32:47]
	ds_read_b64_tr_b16 v[120:121], v169 offset:13952
	ds_read_b64_tr_b16 v[122:123], v169 offset:15104
	v_bfe_i32 v178, v174, 4, 1
	v_bfi_b32 v68, v178, v176, s13
	v_bfe_i32 v179, v174, 5, 1
	v_bfi_b32 v69, v179, v176, s13
	s_waitcnt lgkmcnt(6)
	v_mfma_f32_32x32x16_bf16 v[48:63], v[128:131], v[124:127], v[48:63]
	ds_read_b64_tr_b16 v[124:125], v169 offset:14016
	ds_read_b64_tr_b16 v[126:127], v169 offset:15168
	v_bfe_i32 v178, v174, 6, 1
	v_bfi_b32 v70, v178, v176, s13
	v_bfe_i32 v179, v174, 7, 1
	v_bfi_b32 v71, v179, v176, s13
	s_waitcnt lgkmcnt(6)
	v_mfma_f32_32x32x16_bf16 v[0:15], v[132:135], v[112:115], v[0:15]
	v_bfe_i32 v178, v174, 16, 1
	v_bfi_b32 v72, v178, v176, s13
	v_bfe_i32 v179, v174, 17, 1
	v_bfi_b32 v73, v179, v176, s13
	s_waitcnt lgkmcnt(4)
	v_mfma_f32_32x32x16_bf16 v[16:31], v[132:135], v[116:119], v[16:31]
	v_bfe_i32 v178, v174, 18, 1
	v_bfi_b32 v74, v178, v176, s13
	v_bfe_i32 v179, v174, 19, 1
	v_bfi_b32 v75, v179, v176, s13
	s_waitcnt lgkmcnt(2)
	v_mfma_f32_32x32x16_bf16 v[32:47], v[132:135], v[120:123], v[32:47]
	v_bfe_i32 v178, v174, 20, 1
	v_bfi_b32 v76, v178, v176, s13
	v_bfe_i32 v179, v174, 21, 1
	v_bfi_b32 v77, v179, v176, s13
	s_waitcnt lgkmcnt(0)
	v_mfma_f32_32x32x16_bf16 v[48:63], v[132:135], v[124:127], v[48:63]
	v_bfe_i32 v178, v174, 22, 1
	v_bfi_b32 v78, v178, v176, s13
	v_bfe_i32 v179, v174, 23, 1
	v_bfi_b32 v79, v179, v176, s13
	s_waitcnt lgkmcnt(0)
	s_barrier
	s_mov_b32 s25, s10
	s_mov_b32 s10, s11
	s_mov_b32 s11, s25
	v_add_u32_e32 v172, 8, v172
	s_mov_b32 s9, s24
	s_cmp_lt_u32 s9, s8
	s_cbranch_scc1 .Ldsa_it
; __device__ __forceinline__ unsigned pk2(float lo, float hi) { return pg8::cvt_pk_bf16(lo, hi); }
; __device__ __forceinline__ void dsa_unit(const bf16* QB, const int* SEL, bf16* AO, int b, int kvh, int t, LAS unsigned char* wl, int lane) {
;     ...
;     for (int g = 0; g < 4; ++g) {
;         float m = mx[g];
;         m = __builtin_fmaxf(m, __shfl_xor(m, 1)); m = __builtin_fmaxf(m, __shfl_xor(m, 2)); m = __builtin_fmaxf(m, __shfl_xor(m, 4)); m = __builtin_fmaxf(m, __shfl_xor(m, 8)); m = __builtin_fmaxf(m, __shfl_xor(m, 16));
;         float s = 0.f;
; #pragma unroll
;         for (int kb = 0; kb < 8; ++kb) { const float e = __builtin_amdgcn_exp2f(lg[kb][g] - m); lg[kb][g] = e; s += e; }
;         s += __shfl_xor(s, 1); s += __shfl_xor(s, 2); s += __shfl_xor(s, 4); s += __shfl_xor(s, 8); s += __shfl_xor(s, 16);
;         const float inv = 1.0f / s;
; #pragma unroll
;         for (int kb = 0; kb < 8; ++kb) if ((kb >> 2) == hi) pT[g * 256 + 32 * kb + n] = (bf16)(pk2(lg[kb][g] * inv, 0.f) & 0xffffu);
;     }
;     ...
;     bf16* op = AO + row * D + (kvh * 4) * 128 + 16 * kq + l15;
; #pragma unroll
;     for (int i = 0; i < 2; ++i)
; #pragma unroll
;         for (int g = 0; g < 4; ++g) {
;             const float v = (kq == 0) ? o[4 * i][g] : (kq == 1) ? o[4 * i + 1][g] : (kq == 2) ? o[4 * i + 2][g] : o[4 * i + 3][g];
;             op[g * 128 + 64 * i] = (bf16)(pk2(v, 0.f) & 0xffffu);
;         }
.Ldsa_exit:
	s_waitcnt vmcnt(0)
	v_xor_b32_e32 v178, 32, v206
	v_lshlrev_b32_e32 v178, 2, v178
	ds_bpermute_b32 v179, v178, v173
	s_waitcnt lgkmcnt(0)
	v_add_f32_e32 v173, v173, v179
	v_rcp_f32_e32 v173, v173
	s_nop 0
	v_and_b32_e32 v178, 31, v206
	v_lshlrev_b32_e32 v178, 2, v178
	s_lshl_b32 s24, s0, 7
	s_add_u32 s24, s24, 0x1a000
	v_add_u32_e32 v178, s24, v178
	ds_write_b32 v178, v173
	v_lshl_add_u32 v179, v175, 1, s24
	s_waitcnt lgkmcnt(0)
	ds_read_b128 v[112:115], v179 offset:0
	ds_read_b128 v[116:119], v179 offset:32
	ds_read_b128 v[120:123], v179 offset:64
	ds_read_b128 v[124:127], v179 offset:96
	v_and_b32_e32 v178, 31, v206
	v_lshlrev_b32_e32 v178, 1, v178
	v_mul_u32_u24_e32 v179, 0x88, v175
	v_add3_u32 v178, v178, v179, s45
	v_lshrrev_b32_e32 v179, 4, v206
	v_mul_u32_u24_e32 v182, 0x110, v179
	v_and_b32_e32 v172, 15, v206
	v_lshl_add_u32 v182, v172, 4, v182
	v_add_u32_e32 v174, s45, v182
	s_add_u32 s24, s44, s7
	s_add_u32 s24, s24, s4
	s_lshr_b32 s25, s24, 20
	s_lshl_b32 s24, s24, 12
	s_add_u32 s24, s24, s67
	s_addc_u32 s25, s25, s85
	s_lshl_b32 s26, s5, 10
	s_add_u32 s24, s24, s26
	s_addc_u32 s25, s25, 0
	v_lshlrev_b32_e32 v179, 8, v179
	v_lshl_add_u32 v182, v172, 4, v179
	v_lshl_add_u64 v[144:145], s[24:25], 0, v[182:183]
	s_movk_i32 s26, 0x1000
	s_mov_b32 s27, 0
	s_waitcnt lgkmcnt(0)
	v_pk_mul_f32 v[0:1], v[0:1], v[112:113]
	v_pk_mul_f32 v[2:3], v[2:3], v[114:115]
	v_pk_mul_f32 v[4:5], v[4:5], v[116:117]
	v_pk_mul_f32 v[6:7], v[6:7], v[118:119]
	v_pk_mul_f32 v[8:9], v[8:9], v[120:121]
	v_pk_mul_f32 v[10:11], v[10:11], v[122:123]
	v_pk_mul_f32 v[12:13], v[12:13], v[124:125]
	v_pk_mul_f32 v[14:15], v[14:15], v[126:127]
	v_pk_mul_f32 v[16:17], v[16:17], v[112:113]
	v_pk_mul_f32 v[18:19], v[18:19], v[114:115]
	v_pk_mul_f32 v[20:21], v[20:21], v[116:117]
	v_pk_mul_f32 v[22:23], v[22:23], v[118:119]
	v_pk_mul_f32 v[24:25], v[24:25], v[120:121]
	v_pk_mul_f32 v[26:27], v[26:27], v[122:123]
	v_pk_mul_f32 v[28:29], v[28:29], v[124:125]
	v_pk_mul_f32 v[30:31], v[30:31], v[126:127]
	v_pk_mul_f32 v[32:33], v[32:33], v[112:113]
	v_pk_mul_f32 v[34:35], v[34:35], v[114:115]
	v_pk_mul_f32 v[36:37], v[36:37], v[116:117]
	v_pk_mul_f32 v[38:39], v[38:39], v[118:119]
	v_pk_mul_f32 v[40:41], v[40:41], v[120:121]
	v_pk_mul_f32 v[42:43], v[42:43], v[122:123]
	v_pk_mul_f32 v[44:45], v[44:45], v[124:125]
	v_pk_mul_f32 v[46:47], v[46:47], v[126:127]
	v_pk_mul_f32 v[48:49], v[48:49], v[112:113]
	v_pk_mul_f32 v[50:51], v[50:51], v[114:115]
	v_pk_mul_f32 v[52:53], v[52:53], v[116:117]
	v_pk_mul_f32 v[54:55], v[54:55], v[118:119]
	v_pk_mul_f32 v[56:57], v[56:57], v[120:121]
	v_pk_mul_f32 v[58:59], v[58:59], v[122:123]
	v_pk_mul_f32 v[60:61], v[60:61], v[124:125]
	v_pk_mul_f32 v[62:63], v[62:63], v[126:127]
	v_cvt_pk_bf16_f32 v64, v0, v1
	v_cvt_pk_bf16_f32 v65, v2, v3
	v_cvt_pk_bf16_f32 v66, v4, v5
	v_cvt_pk_bf16_f32 v67, v6, v7
	v_cvt_pk_bf16_f32 v68, v8, v9
	v_cvt_pk_bf16_f32 v69, v10, v11
	v_cvt_pk_bf16_f32 v70, v12, v13
	v_cvt_pk_bf16_f32 v71, v14, v15
	ds_write_b16 v178, v64 offset:0
	ds_write_b16_d16_hi v178, v64 offset:272
	ds_write_b16 v178, v65 offset:544
	ds_write_b16_d16_hi v178, v65 offset:816
	ds_write_b16 v178, v66 offset:2176
	ds_write_b16_d16_hi v178, v66 offset:2448
	ds_write_b16 v178, v67 offset:2720
	ds_write_b16_d16_hi v178, v67 offset:2992
	ds_write_b16 v178, v68 offset:4352
	ds_write_b16_d16_hi v178, v68 offset:4624
	ds_write_b16 v178, v69 offset:4896
	ds_write_b16_d16_hi v178, v69 offset:5168
	ds_write_b16 v178, v70 offset:6528
	ds_write_b16_d16_hi v178, v70 offset:6800
	ds_write_b16 v178, v71 offset:7072
	ds_write_b16_d16_hi v178, v71 offset:7344
	v_cvt_pk_bf16_f32 v72, v16, v17
	v_cvt_pk_bf16_f32 v73, v18, v19
	v_cvt_pk_bf16_f32 v74, v20, v21
	v_cvt_pk_bf16_f32 v75, v22, v23
	v_cvt_pk_bf16_f32 v76, v24, v25
	v_cvt_pk_bf16_f32 v77, v26, v27
	v_cvt_pk_bf16_f32 v78, v28, v29
	v_cvt_pk_bf16_f32 v79, v30, v31
	ds_write_b16 v178, v72 offset:64
	ds_write_b16_d16_hi v178, v72 offset:336
	ds_write_b16 v178, v73 offset:608
	ds_write_b16_d16_hi v178, v73 offset:880
	ds_write_b16 v178, v74 offset:2240
	ds_write_b16_d16_hi v178, v74 offset:2512
	ds_write_b16 v178, v75 offset:2784
	ds_write_b16_d16_hi v178, v75 offset:3056
	ds_write_b16 v178, v76 offset:4416
	ds_write_b16_d16_hi v178, v76 offset:4688
	ds_write_b16 v178, v77 offset:4960
	ds_write_b16_d16_hi v178, v77 offset:5232
	ds_write_b16 v178, v78 offset:6592
	ds_write_b16_d16_hi v178, v78 offset:6864
	ds_write_b16 v178, v79 offset:7136
	ds_write_b16_d16_hi v178, v79 offset:7408
	v_cvt_pk_bf16_f32 v128, v32, v33
	v_cvt_pk_bf16_f32 v129, v34, v35
	v_cvt_pk_bf16_f32 v130, v36, v37
	v_cvt_pk_bf16_f32 v131, v38, v39
	v_cvt_pk_bf16_f32 v132, v40, v41
	v_cvt_pk_bf16_f32 v133, v42, v43
	v_cvt_pk_bf16_f32 v134, v44, v45
	v_cvt_pk_bf16_f32 v135, v46, v47
	ds_write_b16 v178, v128 offset:128
	ds_write_b16_d16_hi v178, v128 offset:400
	ds_write_b16 v178, v129 offset:672
	ds_write_b16_d16_hi v178, v129 offset:944
	ds_write_b16 v178, v130 offset:2304
	ds_write_b16_d16_hi v178, v130 offset:2576
	ds_write_b16 v178, v131 offset:2848
	ds_write_b16_d16_hi v178, v131 offset:3120
	ds_write_b16 v178, v132 offset:4480
	ds_write_b16_d16_hi v178, v132 offset:4752
	ds_write_b16 v178, v133 offset:5024
	ds_write_b16_d16_hi v178, v133 offset:5296
	ds_write_b16 v178, v134 offset:6656
	ds_write_b16_d16_hi v178, v134 offset:6928
	ds_write_b16 v178, v135 offset:7200
	ds_write_b16_d16_hi v178, v135 offset:7472
	v_cvt_pk_bf16_f32 v136, v48, v49
	v_cvt_pk_bf16_f32 v137, v50, v51
	v_cvt_pk_bf16_f32 v138, v52, v53
	v_cvt_pk_bf16_f32 v139, v54, v55
	v_cvt_pk_bf16_f32 v140, v56, v57
	v_cvt_pk_bf16_f32 v141, v58, v59
	v_cvt_pk_bf16_f32 v142, v60, v61
	v_cvt_pk_bf16_f32 v143, v62, v63
	ds_write_b16 v178, v136 offset:192
	ds_write_b16_d16_hi v178, v136 offset:464
	ds_write_b16 v178, v137 offset:736
	ds_write_b16_d16_hi v178, v137 offset:1008
	ds_write_b16 v178, v138 offset:2368
	ds_write_b16_d16_hi v178, v138 offset:2640
	ds_write_b16 v178, v139 offset:2912
	ds_write_b16_d16_hi v178, v139 offset:3184
	ds_write_b16 v178, v140 offset:4544
	ds_write_b16_d16_hi v178, v140 offset:4816
	ds_write_b16 v178, v141 offset:5088
	ds_write_b16_d16_hi v178, v141 offset:5360
	ds_write_b16 v178, v142 offset:6720
	ds_write_b16_d16_hi v178, v142 offset:6992
	ds_write_b16 v178, v143 offset:7264
	ds_write_b16_d16_hi v178, v143 offset:7536
	s_waitcnt lgkmcnt(0)
; __device__ __forceinline__ unsigned pk2(float lo, float hi) { return pg8::cvt_pk_bf16(lo, hi); }
; __device__ __forceinline__ void dsa_unit(const bf16* QB, const int* SEL, bf16* AO, int b, int kvh, int t, LAS unsigned char* wl, int lane) {
;     ...
;     bf16* op = AO + row * D + (kvh * 4) * 128 + 16 * kq + l15;
; #pragma unroll
;     for (int i = 0; i < 2; ++i)
; #pragma unroll
;         for (int g = 0; g < 4; ++g) {
;             const float v = (kq == 0) ? o[4 * i][g] : (kq == 1) ? o[4 * i + 1][g] : (kq == 2) ? o[4 * i + 2][g] : o[4 * i + 3][g];
;             op[g * 128 + 64 * i] = (bf16)(pk2(v, 0.f) & 0xffffu);
;         }
	ds_read_b128 v[80:83], v174 offset:0
	ds_read_b128 v[84:87], v174 offset:1088
	ds_read_b128 v[88:91], v174 offset:2176
	ds_read_b128 v[92:95], v174 offset:3264
	ds_read_b128 v[96:99], v174 offset:4352
	ds_read_b128 v[100:103], v174 offset:5440
	ds_read_b128 v[104:107], v174 offset:6528
	ds_read_b128 v[108:111], v174 offset:7616
	s_waitcnt lgkmcnt(7)
	global_store_dwordx4 v[144:145], v[80:83], off
	v_lshl_add_u64 v[144:145], v[144:145], 0, s[26:27]
	s_waitcnt lgkmcnt(6)
	global_store_dwordx4 v[144:145], v[84:87], off
	v_lshl_add_u64 v[144:145], v[144:145], 0, s[26:27]
	s_waitcnt lgkmcnt(5)
	global_store_dwordx4 v[144:145], v[88:91], off
	v_lshl_add_u64 v[144:145], v[144:145], 0, s[26:27]
	s_waitcnt lgkmcnt(4)
	global_store_dwordx4 v[144:145], v[92:95], off
	v_lshl_add_u64 v[144:145], v[144:145], 0, s[26:27]
	s_waitcnt lgkmcnt(3)
	global_store_dwordx4 v[144:145], v[96:99], off
	v_lshl_add_u64 v[144:145], v[144:145], 0, s[26:27]
	s_waitcnt lgkmcnt(2)
	global_store_dwordx4 v[144:145], v[100:103], off
	v_lshl_add_u64 v[144:145], v[144:145], 0, s[26:27]
	s_waitcnt lgkmcnt(1)
	global_store_dwordx4 v[144:145], v[104:107], off
	v_lshl_add_u64 v[144:145], v[144:145], 0, s[26:27]
	s_waitcnt lgkmcnt(0)
	global_store_dwordx4 v[144:145], v[108:111], off
	s_add_u32 s21, s21, 1
	s_cmp_lt_u32 s21, 2
	s_cbranch_scc1 .Ldsa_half
	s_add_u32 s3, s3, s2
	s_branch .Ldsa_unit
